# SwiGLU epilogue: sigmoid blocks rewritten with packed mul/add (8 blocks, fewer VALU issues, no trans-hazard nops)
# speedup vs baseline: 1.0118x; 1.0060x over previous
.LBB0_425:
	s_lshl_b32 s27, s15, 7
	v_lshl_add_u32 v128, s15, 9, v202
	v_readlane_b32 s15, v254, 46
	ds_read2_b32 v[152:153], v128 offset1:16
	ds_read2_b32 v[150:151], v128 offset0:32 offset1:48
	v_mov_b32_e32 v130, s15
	ds_read_b32 v164, v130
	s_add_i32 s19, s19, s27
	s_and_b64 s[38:39], s[72:73], exec
	s_cselect_b32 s15, 0x200, 0
	v_add_u32_e32 v128, s15, v128
	s_waitcnt lgkmcnt(0)
	v_readfirstlane_b32 s15, v164
	s_cmp_eq_u32 s15, 0
	s_movk_i32 s15, 0x1000
	s_cselect_b32 s15, s15, 0x400
	s_add_i32 s15, s15, 0
	s_lshl_b32 s27, s69, 10
	s_add_i32 s15, s15, s27
	s_lshl_b32 s27, s94, 2
	s_add_i32 s15, s15, s27
	ds_read2_b32 v[148:149], v128 offset1:16
	ds_read2_b32 v[146:147], v128 offset0:32 offset1:48
	v_lshl_add_u32 v128, v194, 2, s15
	v_add_u32_e32 v128, 0x20000, v128
	ds_read_b128 v[142:145], v128
	ds_read_b128 v[138:141], v128 offset:16
	ds_read_b128 v[134:137], v128 offset:512
	ds_read_b128 v[130:133], v128 offset:528
	v_add_u32_e32 v128, s19, v199
	s_cmp_ge_i32 s66, s8
	s_mov_b64 s[46:47], -1
	s_cbranch_scc0 .LBB0_445
	s_cmp_lg_u32 s18, 0
	s_cselect_b64 s[68:69], -1, 0
	s_cmp_eq_u32 s18, 0
	s_waitcnt lgkmcnt(0)
	v_pk_fma_f32 v[156:157], v[126:127], v[152:153], v[144:145] op_sel_hi:[1,0,1]
	v_pk_fma_f32 v[158:159], v[124:125], v[152:153], v[142:143] op_sel_hi:[1,0,1]
	v_pk_fma_f32 v[160:161], v[122:123], v[152:153], v[140:141] op_sel_hi:[1,0,1]
	v_pk_fma_f32 v[162:163], v[120:121], v[152:153], v[138:139] op_sel_hi:[1,0,1]
	s_cbranch_scc1 .LBB0_428
	s_mov_b32 vcc_lo, 0xbfb8aa3b
	v_pk_mul_f32 v[166:167], v[162:163], vcc op_sel_hi:[1,0]
	v_pk_mul_f32 v[154:155], v[158:159], vcc op_sel_hi:[1,0]
	v_pk_mul_f32 v[168:169], v[156:157], vcc op_sel_hi:[1,0]
	v_pk_mul_f32 v[170:171], v[160:161], vcc op_sel_hi:[1,0]
	v_exp_f32_e32 v166, v166
	v_exp_f32_e32 v167, v167
	v_exp_f32_e32 v154, v154
	v_exp_f32_e32 v155, v155
	v_exp_f32_e32 v168, v168
	v_exp_f32_e32 v169, v169
	v_exp_f32_e32 v170, v170
	v_exp_f32_e32 v171, v171
	v_pk_add_f32 v[166:167], v[166:167], 1.0 op_sel_hi:[1,0]
	v_pk_add_f32 v[154:155], v[154:155], 1.0 op_sel_hi:[1,0]
	v_pk_add_f32 v[168:169], v[168:169], 1.0 op_sel_hi:[1,0]
	v_pk_add_f32 v[170:171], v[170:171], 1.0 op_sel_hi:[1,0]
	v_rcp_f32_e32 v166, v166
	v_rcp_f32_e32 v167, v167
	v_rcp_f32_e32 v154, v154
	v_rcp_f32_e32 v155, v155
	v_rcp_f32_e32 v168, v168
	v_rcp_f32_e32 v169, v169
	v_rcp_f32_e32 v170, v170
	v_rcp_f32_e32 v171, v171
	v_pk_mul_f32 v[162:163], v[162:163], v[166:167]
	v_pk_mul_f32 v[158:159], v[158:159], v[154:155]
	v_pk_mul_f32 v[156:157], v[156:157], v[168:169]
	v_pk_mul_f32 v[160:161], v[160:161], v[170:171]
.LBB0_428:
	s_sub_i32 s8, s66, s8
	s_lshl_b32 s8, s8, 7
	s_add_i32 s8, s8, s3
	v_mov_b32_e32 v166, v152
	v_mov_b32_e32 v167, v152
	v_add_u32_e32 v154, s8, v203
	v_mov_b32_e32 v170, v152
	v_mov_b32_e32 v171, v152
	v_ashrrev_i32_e32 v155, 31, v154
	v_pk_fma_f32 v[172:173], v[118:119], v[170:171], v[136:137]
	v_pk_fma_f32 v[174:175], v[116:117], v[166:167], v[134:135]
	v_pk_fma_f32 v[170:171], v[114:115], v[170:171], v[132:133]
	v_pk_fma_f32 v[166:167], v[112:113], v[166:167], v[130:131]
	v_lshl_add_u64 v[154:155], v[154:155], 1, s[62:63]
	v_mad_i64_i32 v[168:169], s[18:19], s23, v128, 0
	v_pk_mul_f32 v[172:173], v[172:173], v[156:157]
	v_pk_mul_f32 v[156:157], v[174:175], v[158:159]
	v_pk_mul_f32 v[160:161], v[170:171], v[160:161]
	v_pk_mul_f32 v[158:159], v[166:167], v[162:163]
	v_lshl_add_u64 v[168:169], v[168:169], 1, v[154:155]
	v_cvt_pk_bf16_f32 v156, v156, v157
	v_cvt_pk_bf16_f32 v157, v172, v173
	v_cvt_pk_bf16_f32 v158, v158, v159
	v_cvt_pk_bf16_f32 v159, v160, v161
	v_mov_b32_e32 v162, v153
	global_store_dwordx4 v[168:169], v[156:159], off
	v_pk_fma_f32 v[160:161], v[106:107], v[162:163], v[140:141] op_sel_hi:[1,0,1]
	s_andn2_b64 vcc, exec, s[68:69]
	v_pk_fma_f32 v[156:157], v[110:111], v[162:163], v[144:145] op_sel_hi:[1,0,1]
	v_pk_fma_f32 v[158:159], v[108:109], v[162:163], v[142:143] op_sel_hi:[1,0,1]
	v_cndmask_b32_e64 v163, 0, 1, s[68:69]
	v_cmp_ne_u32_e64 s[46:47], 1, v163
	v_pk_fma_f32 v[162:163], v[104:105], v[162:163], v[138:139] op_sel_hi:[1,0,1]
	s_cbranch_vccnz .LBB0_430
	s_mov_b32 vcc_lo, 0xbfb8aa3b
	v_pk_mul_f32 v[166:167], v[158:159], vcc op_sel_hi:[1,0]
	v_pk_mul_f32 v[168:169], v[162:163], vcc op_sel_hi:[1,0]
	v_pk_mul_f32 v[170:171], v[156:157], vcc op_sel_hi:[1,0]
	v_pk_mul_f32 v[172:173], v[160:161], vcc op_sel_hi:[1,0]
	v_exp_f32_e32 v166, v166
	v_exp_f32_e32 v167, v167
	v_exp_f32_e32 v168, v168
	v_exp_f32_e32 v169, v169
	v_exp_f32_e32 v170, v170
	v_exp_f32_e32 v171, v171
	v_exp_f32_e32 v172, v172
	v_exp_f32_e32 v173, v173
	v_pk_add_f32 v[166:167], v[166:167], 1.0 op_sel_hi:[1,0]
	v_pk_add_f32 v[168:169], v[168:169], 1.0 op_sel_hi:[1,0]
	v_pk_add_f32 v[170:171], v[170:171], 1.0 op_sel_hi:[1,0]
	v_pk_add_f32 v[172:173], v[172:173], 1.0 op_sel_hi:[1,0]
	v_rcp_f32_e32 v166, v166
	v_rcp_f32_e32 v167, v167
	v_rcp_f32_e32 v168, v168
	v_rcp_f32_e32 v169, v169
	v_rcp_f32_e32 v170, v170
	v_rcp_f32_e32 v171, v171
	v_rcp_f32_e32 v172, v172
	v_rcp_f32_e32 v173, v173
	v_pk_mul_f32 v[158:159], v[158:159], v[166:167]
	v_pk_mul_f32 v[162:163], v[162:163], v[168:169]
	v_pk_mul_f32 v[156:157], v[156:157], v[170:171]
	v_pk_mul_f32 v[160:161], v[160:161], v[172:173]
.LBB0_430:
	v_mov_b32_e32 v166, v153
	v_mov_b32_e32 v167, v153
	v_mov_b32_e32 v170, v153
	v_mov_b32_e32 v171, v153
	v_or_b32_e32 v165, 16, v128
	v_pk_fma_f32 v[172:173], v[102:103], v[170:171], v[136:137]
	v_pk_fma_f32 v[174:175], v[100:101], v[166:167], v[134:135]
	v_pk_fma_f32 v[170:171], v[98:99], v[170:171], v[132:133]
	v_pk_fma_f32 v[166:167], v[96:97], v[166:167], v[130:131]
	v_mad_i64_i32 v[168:169], s[18:19], s23, v165, 0
	v_pk_mul_f32 v[172:173], v[172:173], v[156:157]
	v_pk_mul_f32 v[156:157], v[174:175], v[158:159]
	v_pk_mul_f32 v[160:161], v[170:171], v[160:161]
	v_pk_mul_f32 v[158:159], v[166:167], v[162:163]
	v_lshl_add_u64 v[168:169], v[168:169], 1, v[154:155]
	v_cvt_pk_bf16_f32 v156, v156, v157
	v_cvt_pk_bf16_f32 v157, v172, v173
	v_cvt_pk_bf16_f32 v158, v158, v159
	v_cvt_pk_bf16_f32 v159, v160, v161
	global_store_dwordx4 v[168:169], v[156:159], off
	v_pk_fma_f32 v[160:161], v[90:91], v[150:151], v[140:141] op_sel_hi:[1,0,1]
	s_and_b64 vcc, exec, s[46:47]
	v_pk_fma_f32 v[156:157], v[94:95], v[150:151], v[144:145] op_sel_hi:[1,0,1]
	v_pk_fma_f32 v[158:159], v[92:93], v[150:151], v[142:143] op_sel_hi:[1,0,1]
	v_pk_fma_f32 v[162:163], v[88:89], v[150:151], v[138:139] op_sel_hi:[1,0,1]
	s_cbranch_vccnz .LBB0_432
	s_mov_b32 vcc_lo, 0xbfb8aa3b
	v_pk_mul_f32 v[166:167], v[158:159], vcc op_sel_hi:[1,0]
	v_pk_mul_f32 v[168:169], v[162:163], vcc op_sel_hi:[1,0]
	v_pk_mul_f32 v[170:171], v[156:157], vcc op_sel_hi:[1,0]
	v_pk_mul_f32 v[172:173], v[160:161], vcc op_sel_hi:[1,0]
	v_exp_f32_e32 v166, v166
	v_exp_f32_e32 v167, v167
	v_exp_f32_e32 v168, v168
	v_exp_f32_e32 v169, v169
	v_exp_f32_e32 v170, v170
	v_exp_f32_e32 v171, v171
	v_exp_f32_e32 v172, v172
	v_exp_f32_e32 v173, v173
	v_pk_add_f32 v[166:167], v[166:167], 1.0 op_sel_hi:[1,0]
	v_pk_add_f32 v[168:169], v[168:169], 1.0 op_sel_hi:[1,0]
	v_pk_add_f32 v[170:171], v[170:171], 1.0 op_sel_hi:[1,0]
	v_pk_add_f32 v[172:173], v[172:173], 1.0 op_sel_hi:[1,0]
	v_rcp_f32_e32 v166, v166
	v_rcp_f32_e32 v167, v167
	v_rcp_f32_e32 v168, v168
	v_rcp_f32_e32 v169, v169
	v_rcp_f32_e32 v170, v170
	v_rcp_f32_e32 v171, v171
	v_rcp_f32_e32 v172, v172
	v_rcp_f32_e32 v173, v173
	v_pk_mul_f32 v[158:159], v[158:159], v[166:167]
	v_pk_mul_f32 v[162:163], v[162:163], v[168:169]
	v_pk_mul_f32 v[156:157], v[156:157], v[170:171]
	v_pk_mul_f32 v[160:161], v[160:161], v[172:173]
.LBB0_432:
	v_mov_b32_e32 v166, v150
	v_mov_b32_e32 v167, v150
	v_mov_b32_e32 v170, v150
	v_mov_b32_e32 v171, v150
	v_or_b32_e32 v165, 32, v128
	v_pk_fma_f32 v[172:173], v[86:87], v[170:171], v[136:137]
	v_pk_fma_f32 v[174:175], v[84:85], v[166:167], v[134:135]
	v_pk_fma_f32 v[170:171], v[82:83], v[170:171], v[132:133]
	v_pk_fma_f32 v[166:167], v[80:81], v[166:167], v[130:131]
	v_mad_i64_i32 v[168:169], s[18:19], s23, v165, 0
	v_pk_mul_f32 v[172:173], v[172:173], v[156:157]
	v_pk_mul_f32 v[156:157], v[174:175], v[158:159]
	v_pk_mul_f32 v[160:161], v[170:171], v[160:161]
	v_pk_mul_f32 v[158:159], v[166:167], v[162:163]
	v_lshl_add_u64 v[168:169], v[168:169], 1, v[154:155]
	v_cvt_pk_bf16_f32 v156, v156, v157
	v_cvt_pk_bf16_f32 v157, v172, v173
	v_cvt_pk_bf16_f32 v158, v158, v159
	v_cvt_pk_bf16_f32 v159, v160, v161
	v_mov_b32_e32 v162, v151
	global_store_dwordx4 v[168:169], v[156:159], off
	v_pk_fma_f32 v[160:161], v[74:75], v[162:163], v[140:141] op_sel_hi:[1,0,1]
	s_and_b64 vcc, exec, s[46:47]
	v_pk_fma_f32 v[156:157], v[78:79], v[162:163], v[144:145] op_sel_hi:[1,0,1]
	v_pk_fma_f32 v[158:159], v[76:77], v[162:163], v[142:143] op_sel_hi:[1,0,1]
	v_pk_fma_f32 v[162:163], v[72:73], v[162:163], v[138:139] op_sel_hi:[1,0,1]
	s_cbranch_vccnz .LBB0_434
	s_mov_b32 vcc_lo, 0xbfb8aa3b
	v_pk_mul_f32 v[166:167], v[158:159], vcc op_sel_hi:[1,0]
	v_pk_mul_f32 v[168:169], v[162:163], vcc op_sel_hi:[1,0]
	v_pk_mul_f32 v[170:171], v[156:157], vcc op_sel_hi:[1,0]
	v_pk_mul_f32 v[172:173], v[160:161], vcc op_sel_hi:[1,0]
	v_exp_f32_e32 v166, v166
	v_exp_f32_e32 v167, v167
	v_exp_f32_e32 v168, v168
	v_exp_f32_e32 v169, v169
	v_exp_f32_e32 v170, v170
	v_exp_f32_e32 v171, v171
	v_exp_f32_e32 v172, v172
	v_exp_f32_e32 v173, v173
	v_pk_add_f32 v[166:167], v[166:167], 1.0 op_sel_hi:[1,0]
	v_pk_add_f32 v[168:169], v[168:169], 1.0 op_sel_hi:[1,0]
	v_pk_add_f32 v[170:171], v[170:171], 1.0 op_sel_hi:[1,0]
	v_pk_add_f32 v[172:173], v[172:173], 1.0 op_sel_hi:[1,0]
	v_rcp_f32_e32 v166, v166
	v_rcp_f32_e32 v167, v167
	v_rcp_f32_e32 v168, v168
	v_rcp_f32_e32 v169, v169
	v_rcp_f32_e32 v170, v170
	v_rcp_f32_e32 v171, v171
	v_rcp_f32_e32 v172, v172
	v_rcp_f32_e32 v173, v173
	v_pk_mul_f32 v[158:159], v[158:159], v[166:167]
	v_pk_mul_f32 v[162:163], v[162:163], v[168:169]
	v_pk_mul_f32 v[156:157], v[156:157], v[170:171]
	v_pk_mul_f32 v[160:161], v[160:161], v[172:173]
.LBB0_434:
	v_mov_b32_e32 v166, v151
	v_mov_b32_e32 v167, v151
	v_mov_b32_e32 v170, v151
	v_mov_b32_e32 v171, v151
	v_or_b32_e32 v165, 48, v128
	v_pk_fma_f32 v[172:173], v[70:71], v[170:171], v[136:137]
	v_pk_fma_f32 v[174:175], v[68:69], v[166:167], v[134:135]
	v_pk_fma_f32 v[170:171], v[66:67], v[170:171], v[132:133]
	v_pk_fma_f32 v[166:167], v[64:65], v[166:167], v[130:131]
	v_mad_i64_i32 v[168:169], s[18:19], s23, v165, 0
	v_pk_mul_f32 v[172:173], v[172:173], v[156:157]
	v_pk_mul_f32 v[156:157], v[174:175], v[158:159]
	v_pk_mul_f32 v[160:161], v[170:171], v[160:161]
	v_pk_mul_f32 v[158:159], v[166:167], v[162:163]
	v_lshl_add_u64 v[168:169], v[168:169], 1, v[154:155]
	v_cvt_pk_bf16_f32 v156, v156, v157
	v_cvt_pk_bf16_f32 v157, v172, v173
	v_cvt_pk_bf16_f32 v158, v158, v159
	v_cvt_pk_bf16_f32 v159, v160, v161
	s_and_b64 vcc, exec, s[44:45]
	global_store_dwordx4 v[168:169], v[156:159], off
	s_cbranch_vccnz .LBB0_444
	s_nop 0
	v_pk_fma_f32 v[156:157], v[62:63], v[148:149], v[144:145] op_sel_hi:[1,0,1]
	v_pk_fma_f32 v[158:159], v[60:61], v[148:149], v[142:143] op_sel_hi:[1,0,1]
	v_pk_fma_f32 v[160:161], v[58:59], v[148:149], v[140:141] op_sel_hi:[1,0,1]
	s_and_b64 vcc, exec, s[46:47]
	v_pk_fma_f32 v[162:163], v[56:57], v[148:149], v[138:139] op_sel_hi:[1,0,1]
	s_cbranch_vccnz .LBB0_437
	s_mov_b32 vcc_lo, 0xbfb8aa3b
	v_pk_mul_f32 v[166:167], v[158:159], vcc op_sel_hi:[1,0]
	v_pk_mul_f32 v[168:169], v[162:163], vcc op_sel_hi:[1,0]
	v_pk_mul_f32 v[170:171], v[156:157], vcc op_sel_hi:[1,0]
	v_pk_mul_f32 v[172:173], v[160:161], vcc op_sel_hi:[1,0]
	v_exp_f32_e32 v166, v166
	v_exp_f32_e32 v167, v167
	v_exp_f32_e32 v168, v168
	v_exp_f32_e32 v169, v169
	v_exp_f32_e32 v170, v170
	v_exp_f32_e32 v171, v171
	v_exp_f32_e32 v172, v172
	v_exp_f32_e32 v173, v173
	v_pk_add_f32 v[166:167], v[166:167], 1.0 op_sel_hi:[1,0]
	v_pk_add_f32 v[168:169], v[168:169], 1.0 op_sel_hi:[1,0]
	v_pk_add_f32 v[170:171], v[170:171], 1.0 op_sel_hi:[1,0]
	v_pk_add_f32 v[172:173], v[172:173], 1.0 op_sel_hi:[1,0]
	v_rcp_f32_e32 v166, v166
	v_rcp_f32_e32 v167, v167
	v_rcp_f32_e32 v168, v168
	v_rcp_f32_e32 v169, v169
	v_rcp_f32_e32 v170, v170
	v_rcp_f32_e32 v171, v171
	v_rcp_f32_e32 v172, v172
	v_rcp_f32_e32 v173, v173
	v_pk_mul_f32 v[158:159], v[158:159], v[166:167]
	v_pk_mul_f32 v[162:163], v[162:163], v[168:169]
	v_pk_mul_f32 v[156:157], v[156:157], v[170:171]
	v_pk_mul_f32 v[160:161], v[160:161], v[172:173]
.LBB0_437:
	v_mov_b32_e32 v166, v148
	v_mov_b32_e32 v167, v148
	v_mov_b32_e32 v170, v148
	v_mov_b32_e32 v171, v148
	v_add_u32_e32 v165, 0x80, v128
	v_pk_fma_f32 v[172:173], v[54:55], v[170:171], v[136:137]
	v_pk_fma_f32 v[174:175], v[52:53], v[166:167], v[134:135]
	v_pk_fma_f32 v[170:171], v[50:51], v[170:171], v[132:133]
	v_pk_fma_f32 v[166:167], v[48:49], v[166:167], v[130:131]
	v_mad_i64_i32 v[168:169], s[18:19], s23, v165, 0
	v_pk_mul_f32 v[172:173], v[172:173], v[156:157]
	v_pk_mul_f32 v[156:157], v[174:175], v[158:159]
	v_pk_mul_f32 v[160:161], v[170:171], v[160:161]
	v_pk_mul_f32 v[158:159], v[166:167], v[162:163]
	v_lshl_add_u64 v[168:169], v[168:169], 1, v[154:155]
	v_cvt_pk_bf16_f32 v156, v156, v157
	v_cvt_pk_bf16_f32 v157, v172, v173
	v_cvt_pk_bf16_f32 v158, v158, v159
	v_cvt_pk_bf16_f32 v159, v160, v161
	v_mov_b32_e32 v162, v149
	global_store_dwordx4 v[168:169], v[156:159], off
	v_pk_fma_f32 v[160:161], v[42:43], v[162:163], v[140:141] op_sel_hi:[1,0,1]
	s_and_b64 vcc, exec, s[46:47]
	v_pk_fma_f32 v[156:157], v[46:47], v[162:163], v[144:145] op_sel_hi:[1,0,1]
	v_pk_fma_f32 v[158:159], v[44:45], v[162:163], v[142:143] op_sel_hi:[1,0,1]
	v_pk_fma_f32 v[162:163], v[40:41], v[162:163], v[138:139] op_sel_hi:[1,0,1]
	s_cbranch_vccnz .LBB0_439
	s_mov_b32 vcc_lo, 0xbfb8aa3b
	v_pk_mul_f32 v[166:167], v[158:159], vcc op_sel_hi:[1,0]
	v_pk_mul_f32 v[168:169], v[162:163], vcc op_sel_hi:[1,0]
	v_pk_mul_f32 v[170:171], v[156:157], vcc op_sel_hi:[1,0]
	v_pk_mul_f32 v[172:173], v[160:161], vcc op_sel_hi:[1,0]
	v_exp_f32_e32 v166, v166
	v_exp_f32_e32 v167, v167
	v_exp_f32_e32 v168, v168
	v_exp_f32_e32 v169, v169
	v_exp_f32_e32 v170, v170
	v_exp_f32_e32 v171, v171
	v_exp_f32_e32 v172, v172
	v_exp_f32_e32 v173, v173
	v_pk_add_f32 v[166:167], v[166:167], 1.0 op_sel_hi:[1,0]
	v_pk_add_f32 v[168:169], v[168:169], 1.0 op_sel_hi:[1,0]
	v_pk_add_f32 v[170:171], v[170:171], 1.0 op_sel_hi:[1,0]
	v_pk_add_f32 v[172:173], v[172:173], 1.0 op_sel_hi:[1,0]
	v_rcp_f32_e32 v166, v166
	v_rcp_f32_e32 v167, v167
	v_rcp_f32_e32 v168, v168
	v_rcp_f32_e32 v169, v169
	v_rcp_f32_e32 v170, v170
	v_rcp_f32_e32 v171, v171
	v_rcp_f32_e32 v172, v172
	v_rcp_f32_e32 v173, v173
	v_pk_mul_f32 v[158:159], v[158:159], v[166:167]
	v_pk_mul_f32 v[162:163], v[162:163], v[168:169]
	v_pk_mul_f32 v[156:157], v[156:157], v[170:171]
	v_pk_mul_f32 v[160:161], v[160:161], v[172:173]
.LBB0_439:
	v_mov_b32_e32 v166, v149
	v_mov_b32_e32 v167, v149
	v_mov_b32_e32 v170, v149
	v_mov_b32_e32 v171, v149
	v_or_b32_e32 v168, 16, v165
	v_pk_fma_f32 v[172:173], v[38:39], v[170:171], v[136:137]
	v_pk_fma_f32 v[174:175], v[36:37], v[166:167], v[134:135]
	v_pk_fma_f32 v[170:171], v[34:35], v[170:171], v[132:133]
	v_pk_fma_f32 v[166:167], v[32:33], v[166:167], v[130:131]
	v_mad_i64_i32 v[168:169], s[18:19], s23, v168, 0
	v_pk_mul_f32 v[172:173], v[172:173], v[156:157]
	v_pk_mul_f32 v[156:157], v[174:175], v[158:159]
	v_pk_mul_f32 v[160:161], v[170:171], v[160:161]
	v_pk_mul_f32 v[158:159], v[166:167], v[162:163]
	v_lshl_add_u64 v[168:169], v[168:169], 1, v[154:155]
	v_cvt_pk_bf16_f32 v156, v156, v157
	v_cvt_pk_bf16_f32 v157, v172, v173
	v_cvt_pk_bf16_f32 v158, v158, v159
	v_cvt_pk_bf16_f32 v159, v160, v161
	global_store_dwordx4 v[168:169], v[156:159], off
	v_pk_fma_f32 v[160:161], v[26:27], v[146:147], v[140:141] op_sel_hi:[1,0,1]
	s_and_b64 vcc, exec, s[46:47]
	v_pk_fma_f32 v[156:157], v[30:31], v[146:147], v[144:145] op_sel_hi:[1,0,1]
	v_pk_fma_f32 v[158:159], v[28:29], v[146:147], v[142:143] op_sel_hi:[1,0,1]
	v_pk_fma_f32 v[162:163], v[24:25], v[146:147], v[138:139] op_sel_hi:[1,0,1]
	s_cbranch_vccnz .LBB0_441
	s_mov_b32 vcc_lo, 0xbfb8aa3b
	v_pk_mul_f32 v[166:167], v[158:159], vcc op_sel_hi:[1,0]
	v_pk_mul_f32 v[168:169], v[162:163], vcc op_sel_hi:[1,0]
	v_pk_mul_f32 v[170:171], v[156:157], vcc op_sel_hi:[1,0]
	v_pk_mul_f32 v[172:173], v[160:161], vcc op_sel_hi:[1,0]
	v_exp_f32_e32 v166, v166
	v_exp_f32_e32 v167, v167
	v_exp_f32_e32 v168, v168
	v_exp_f32_e32 v169, v169
	v_exp_f32_e32 v170, v170
	v_exp_f32_e32 v171, v171
	v_exp_f32_e32 v172, v172
	v_exp_f32_e32 v173, v173
	v_pk_add_f32 v[166:167], v[166:167], 1.0 op_sel_hi:[1,0]
	v_pk_add_f32 v[168:169], v[168:169], 1.0 op_sel_hi:[1,0]
	v_pk_add_f32 v[170:171], v[170:171], 1.0 op_sel_hi:[1,0]
	v_pk_add_f32 v[172:173], v[172:173], 1.0 op_sel_hi:[1,0]
	v_rcp_f32_e32 v166, v166
	v_rcp_f32_e32 v167, v167
	v_rcp_f32_e32 v168, v168
	v_rcp_f32_e32 v169, v169
	v_rcp_f32_e32 v170, v170
	v_rcp_f32_e32 v171, v171
	v_rcp_f32_e32 v172, v172
	v_rcp_f32_e32 v173, v173
	v_pk_mul_f32 v[158:159], v[158:159], v[166:167]
	v_pk_mul_f32 v[162:163], v[162:163], v[168:169]
	v_pk_mul_f32 v[156:157], v[156:157], v[170:171]
	v_pk_mul_f32 v[160:161], v[160:161], v[172:173]
.LBB0_441:
	v_mov_b32_e32 v166, v146
	v_mov_b32_e32 v167, v146
	v_mov_b32_e32 v170, v146
	v_mov_b32_e32 v171, v146
	v_or_b32_e32 v168, 32, v165
	v_pk_fma_f32 v[172:173], v[22:23], v[170:171], v[136:137]
	v_pk_fma_f32 v[174:175], v[20:21], v[166:167], v[134:135]
	v_pk_fma_f32 v[170:171], v[18:19], v[170:171], v[132:133]
	v_pk_fma_f32 v[166:167], v[16:17], v[166:167], v[130:131]
	v_mad_i64_i32 v[168:169], s[18:19], s23, v168, 0
	v_pk_mul_f32 v[172:173], v[172:173], v[156:157]
	v_pk_mul_f32 v[156:157], v[174:175], v[158:159]
	v_pk_mul_f32 v[160:161], v[170:171], v[160:161]
	v_pk_mul_f32 v[158:159], v[166:167], v[162:163]
	v_lshl_add_u64 v[168:169], v[168:169], 1, v[154:155]
	v_cvt_pk_bf16_f32 v156, v156, v157
	v_cvt_pk_bf16_f32 v157, v172, v173
	v_cvt_pk_bf16_f32 v158, v158, v159
	v_cvt_pk_bf16_f32 v159, v160, v161
	v_mov_b32_e32 v162, v147
	global_store_dwordx4 v[168:169], v[156:159], off
	v_pk_fma_f32 v[160:161], v[10:11], v[162:163], v[140:141] op_sel_hi:[1,0,1]
	s_and_b64 vcc, exec, s[46:47]
	v_pk_fma_f32 v[156:157], v[14:15], v[162:163], v[144:145] op_sel_hi:[1,0,1]
	v_pk_fma_f32 v[158:159], v[12:13], v[162:163], v[142:143] op_sel_hi:[1,0,1]
	v_pk_fma_f32 v[162:163], v[8:9], v[162:163], v[138:139] op_sel_hi:[1,0,1]
	s_cbranch_vccnz .LBB0_443
	s_mov_b32 vcc_lo, 0xbfb8aa3b
	v_pk_mul_f32 v[166:167], v[158:159], vcc op_sel_hi:[1,0]
	v_pk_mul_f32 v[168:169], v[162:163], vcc op_sel_hi:[1,0]
	v_pk_mul_f32 v[170:171], v[156:157], vcc op_sel_hi:[1,0]
	v_pk_mul_f32 v[172:173], v[160:161], vcc op_sel_hi:[1,0]
	v_exp_f32_e32 v166, v166
	v_exp_f32_e32 v167, v167
	v_exp_f32_e32 v168, v168
	v_exp_f32_e32 v169, v169
	v_exp_f32_e32 v170, v170
	v_exp_f32_e32 v171, v171
	v_exp_f32_e32 v172, v172
	v_exp_f32_e32 v173, v173
	v_pk_add_f32 v[166:167], v[166:167], 1.0 op_sel_hi:[1,0]
	v_pk_add_f32 v[168:169], v[168:169], 1.0 op_sel_hi:[1,0]
	v_pk_add_f32 v[170:171], v[170:171], 1.0 op_sel_hi:[1,0]
	v_pk_add_f32 v[172:173], v[172:173], 1.0 op_sel_hi:[1,0]
	v_rcp_f32_e32 v166, v166
	v_rcp_f32_e32 v167, v167
	v_rcp_f32_e32 v168, v168
	v_rcp_f32_e32 v169, v169
	v_rcp_f32_e32 v170, v170
	v_rcp_f32_e32 v171, v171
	v_rcp_f32_e32 v172, v172
	v_rcp_f32_e32 v173, v173
	v_pk_mul_f32 v[158:159], v[158:159], v[166:167]
	v_pk_mul_f32 v[162:163], v[162:163], v[168:169]
	v_pk_mul_f32 v[156:157], v[156:157], v[170:171]
	v_pk_mul_f32 v[160:161], v[160:161], v[172:173]
